# split-MERGE fixup moved before the step grid barrier behind a 64-workgroup barrier; separate fixup pass and one grid barrier per layer dropped
# baseline (speedup 1.0000x reference)
; __device__ __forceinline__ unsigned pk2(float lo, float hi) { return f2bf(lo) | (f2bf(hi) << 16); }
; __device__ __forceinline__ float bflo(unsigned w) { return __uint_as_float(w << 16); }
; __device__ __forceinline__ float bfhi(unsigned w) { return __uint_as_float(w & 0xffff0000u); }
; __global__ void __launch_bounds__(NTHR, 2) hybrid_fwd(Params p) {
;     ...
;                 if (step < 2) xcd_barrier(bar);
;                 if (split && step == 1) {
;                     const bf16* P0 = (const bf16*)(ws + WS_HL); const bf16* P1 = P0 + (size_t)MT * DM; bf16* MG = (bf16*)(ws + WS_PP);
;                     for (int it = c * NTHR + (int)threadIdx.x; it < 1024 * 256; it += G * NTHR) { const size_t r = (size_t)(NP + (it >> 8)); const int c8 = (it & 255) * 8;
;                         const v4u a = *(const v4u*)(P0 + r * DM + c8), b = *(const v4u*)(P1 + r * DM + c8), gq = *(const v4u*)(PROJ + r * NC + C_MB + c8);
;                         v4u o;
;                         o.x = pk2(fmaxf(bflo(gq.x), 1e-30f) * (bflo(a.x) + bflo(b.x)), fmaxf(bfhi(gq.x), 1e-30f) * (bfhi(a.x) + bfhi(b.x)));
;                         o.y = pk2(fmaxf(bflo(gq.y), 1e-30f) * (bflo(a.y) + bflo(b.y)), fmaxf(bfhi(gq.y), 1e-30f) * (bfhi(a.y) + bfhi(b.y)));
;                         o.z = pk2(fmaxf(bflo(gq.z), 1e-30f) * (bflo(a.z) + bflo(b.z)), fmaxf(bfhi(gq.z), 1e-30f) * (bfhi(a.z) + bfhi(b.z)));
;                         o.w = pk2(fmaxf(bflo(gq.w), 1e-30f) * (bflo(a.w) + bflo(b.w)), fmaxf(bfhi(gq.w), 1e-30f) * (bfhi(a.w) + bfhi(b.w)));
;                         *(v4u*)(MG + r * DM + c8) = o; }
;                     xcd_barrier(bar);
.LBB0_860:
	s_andn2_b64 vcc, exec, s[18:19]
	s_cbranch_vccnz .LBB0_915
	s_cmp_lg_u32 s51, 1
	s_cbranch_scc1 .Lsf_done
	v_readlane_b32 s98, v249, 58
	v_readlane_b32 s99, v249, 59
	s_nop 1
	s_and_b64 vcc, exec, s[98:99]
	s_cbranch_vccnz .Lsf_done
	v_readlane_b32 s100, v251, 0
	s_nop 1
	s_cmp_gt_u32 s100, 63
	s_cbranch_scc1 .Lsf_done
	s_waitcnt vmcnt(0) lgkmcnt(0)
	s_barrier
	v_readlane_b32 s98, v251, 19
	v_readlane_b32 s99, v251, 20
	v_readlane_b32 s100, v250, 58
	v_readlane_b32 s101, v250, 59
	s_nop 1
	s_and_b64 vcc, exec, s[98:99]
	s_and_saveexec_b64 s[98:99], vcc
	s_cbranch_execz .Lsf_join
	buffer_wbl2 sc1
	s_waitcnt vmcnt(0)
	v_mov_b32_e32 v2, 1
	v_mov_b32_e32 v4, 0
	s_nop 4
	global_atomic_add v3, v1, v2, s[100:101] offset:256 sc0
	s_waitcnt vmcnt(0)
	v_and_b32_e32 v3, 0xffffffc0, v3
	v_add_u32_e32 v3, 64, v3
.Lsf_spin:
	global_load_dword v2, v1, s[100:101] offset:256 sc1
	s_waitcnt vmcnt(0)
	v_cmp_ge_u32_e32 vcc, v2, v3
	s_cbranch_vccnz .Lsf_go
	s_sleep 1
	v_add_u32_e32 v4, 1, v4
	v_cmp_gt_u32_e32 vcc, 0x8000, v4
	s_cbranch_vccnz .Lsf_spin
.Lsf_go:
	buffer_inv sc1
	s_waitcnt vmcnt(0)
.Lsf_join:
	s_or_b64 exec, exec, s[98:99]
	s_barrier
	s_mov_b64 s[0:1], exec
	v_readlane_b32 s2, v248, 10
	v_readlane_b32 s3, v248, 11
	s_nop 1
	s_and_b64 s[2:3], s[0:1], s[2:3]
	s_mov_b64 exec, s[2:3]
	s_cbranch_execz .Lsf_loopend
	s_mov_b64 s[18:19], 0
	v_mov_b32_e32 v2, v209
	v_mov_b32_e32 v3, v207
.Lsf_loop:
	v_ashrrev_i32_e32 v0, 8, v3
	v_add_u32_e32 v12, 0x2000, v0
	v_ashrrev_i32_e32 v13, 31, v12
	v_and_b32_e32 v0, 0x7f8, v2
	v_mov_b64_e32 v[14:15], s[8:9]
	v_lshlrev_b64 v[16:17], 12, v[12:13]
	v_lshlrev_b32_e32 v0, 1, v0
	v_mad_i64_i32 v[12:13], s[2:3], v12, s25, v[14:15]
	v_lshl_add_u64 v[12:13], v[12:13], 0, v[0:1]
	v_lshl_add_u64 v[4:5], s[46:47], 0, v[16:17]
	v_lshl_add_u64 v[8:9], s[56:57], 0, v[16:17]
	v_add_co_u32_e32 v12, vcc, s22, v12
	v_lshl_add_u64 v[4:5], v[4:5], 0, v[0:1]
	v_lshl_add_u64 v[8:9], v[8:9], 0, v[0:1]
	v_addc_co_u32_e32 v13, vcc, 0, v13, vcc
	global_load_dwordx4 v[4:7], v[4:5], off
	s_mov_b32 s2, 0x37fff
	global_load_dwordx4 v[8:11], v[8:9], off
	v_cmp_lt_i32_e32 vcc, s2, v3
	global_load_dwordx4 v[12:15], v[12:13], off
	v_add_u32_e32 v2, 0x40000, v2
	s_or_b64 s[18:19], vcc, s[18:19]
	s_waitcnt vmcnt(0) lgkmcnt(0)
	v_lshlrev_b32_e32 v21, 16, v5
	v_lshlrev_b32_e32 v20, 16, v4
	v_lshlrev_b32_e32 v23, 16, v9
	v_lshlrev_b32_e32 v22, 16, v8
	v_lshlrev_b32_e32 v18, 16, v12
	v_and_b32_e32 v12, 0xffff0000, v12
	v_lshlrev_b32_e32 v19, 16, v13
	v_and_b32_e32 v13, 0xffff0000, v13
	v_and_b32_e32 v5, 0xffff0000, v5
	v_and_b32_e32 v4, 0xffff0000, v4
	v_and_b32_e32 v9, 0xffff0000, v9
	v_and_b32_e32 v8, 0xffff0000, v8
	v_max_f32_e32 v12, v12, v12
	v_max_f32_e32 v13, v13, v13
	v_pk_add_f32 v[4:5], v[4:5], v[8:9]
	v_and_b32_e32 v9, 0xffff0000, v14
	v_max_f32_e32 v18, v18, v18
	v_max_f32_e32 v12, 0xda24260, v12
	v_max_f32_e32 v19, v19, v19
	v_max_f32_e32 v13, 0xda24260, v13
	v_max_f32_e32 v9, v9, v9
	v_max_f32_e32 v18, 0xda24260, v18
	v_max_f32_e32 v19, 0xda24260, v19
	v_pk_add_f32 v[20:21], v[20:21], v[22:23]
	v_pk_mul_f32 v[4:5], v[4:5], v[12:13]
	v_lshlrev_b32_e32 v8, 16, v14
	v_max_f32_e32 v12, 0xda24260, v9
	v_lshlrev_b32_e32 v9, 16, v15
	v_and_b32_e32 v13, 0xffff0000, v15
	v_pk_mul_f32 v[18:19], v[20:21], v[18:19]
	v_max_f32_e32 v8, v8, v8
	v_max_f32_e32 v9, v9, v9
	v_max_f32_e32 v13, v13, v13
	v_lshlrev_b32_e32 v15, 16, v7
	v_lshlrev_b32_e32 v14, 16, v6
	v_lshlrev_b32_e32 v21, 16, v11
	v_lshlrev_b32_e32 v20, 16, v10
	v_and_b32_e32 v7, 0xffff0000, v7
	v_and_b32_e32 v6, 0xffff0000, v6
	v_and_b32_e32 v11, 0xffff0000, v11
	v_and_b32_e32 v10, 0xffff0000, v10
	v_max_f32_e32 v8, 0xda24260, v8
	v_max_f32_e32 v9, 0xda24260, v9
	v_max_f32_e32 v13, 0xda24260, v13
	v_pk_add_f32 v[14:15], v[14:15], v[20:21]
	v_pk_add_f32 v[6:7], v[6:7], v[10:11]
	v_pk_mul_f32 v[8:9], v[14:15], v[8:9]
	v_pk_mul_f32 v[6:7], v[6:7], v[12:13]
	v_bfe_u32 v12, v5, 16, 1
	v_bfe_u32 v13, v4, 16, 1
	v_add3_u32 v4, v4, v13, s26
	v_add3_u32 v5, v5, v12, s26
	v_bfe_u32 v12, v8, 16, 1
	v_bfe_u32 v13, v9, 16, 1
	v_bfe_u32 v10, v7, 16, 1
	v_bfe_u32 v11, v6, 16, 1
	v_add3_u32 v9, v9, v13, s26
	v_add3_u32 v8, v8, v12, s26
	v_add3_u32 v6, v6, v11, s26
	v_add3_u32 v7, v7, v10, s26
	v_bfe_u32 v10, v18, 16, 1
	v_bfe_u32 v11, v19, 16, 1
	v_lshrrev_b32_e32 v8, 16, v8
	v_lshrrev_b32_e32 v9, 16, v9
	v_add3_u32 v11, v19, v11, s26
	v_add3_u32 v10, v18, v10, s26
	v_and_or_b32 v7, v7, s24, v9
	v_and_or_b32 v6, v6, s24, v8
	v_lshl_add_u64 v[8:9], s[58:59], 0, v[16:17]
	v_lshrrev_b32_e32 v10, 16, v10
	v_lshrrev_b32_e32 v11, 16, v11
	v_lshl_add_u64 v[8:9], v[8:9], 0, v[0:1]
	v_add_u32_e32 v0, 0x8000, v3
	v_and_or_b32 v5, v5, s24, v11
	v_and_or_b32 v4, v4, s24, v10
	v_mov_b32_e32 v3, v0
	global_store_dwordx4 v[8:9], v[4:7], off
	s_andn2_b64 exec, exec, s[18:19]
	s_cbranch_execnz .Lsf_loop

; __device__ __forceinline__ void xcd_barrier(const XcdBarrier& b) {
;     asm volatile("s_waitcnt vmcnt(0)" ::: "memory");
;     __syncthreads();
;     if (threadIdx.x == 0) {
;         unsigned* bar = b.bar;
;         __builtin_amdgcn_s_waitcnt(0);
;         unsigned nloc = b.st[0], nx = b.st[1];
;         if (nloc == 0u) { xcd_barrier_complete(bar, b.x, nloc, nx); b.st[0] = nloc; b.st[1] = nx; }
.Lsf_done:
	s_waitcnt vmcnt(0)
	s_waitcnt vmcnt(0) lgkmcnt(0)
	s_barrier
	s_mov_b64 s[0:1], exec
	v_readlane_b32 s2, v251, 19
	v_readlane_b32 s3, v251, 20
	s_and_b64 s[2:3], s[0:1], s[2:3]
	s_mov_b64 exec, s[2:3]
	s_cbranch_execz .LBB0_914
	v_readlane_b32 s2, v248, 1
	s_waitcnt vmcnt(0) expcnt(0) lgkmcnt(0)
	s_nop 0
	v_mov_b32_e32 v0, s2
	ds_read_b32 v3, v0
	v_readlane_b32 s2, v248, 2
	s_waitcnt lgkmcnt(0)
	v_cmp_ne_u32_e32 vcc, 0, v3
	v_mov_b32_e32 v0, s2
	ds_read_b32 v2, v0
	s_cbranch_vccnz .LBB0_878
	s_mov_b32 s2, 1
	s_branch .LBB0_865

; __device__ __forceinline__ unsigned pk2(float lo, float hi) { return f2bf(lo) | (f2bf(hi) << 16); }
; __device__ __forceinline__ float bflo(unsigned w) { return __uint_as_float(w << 16); }
; __device__ __forceinline__ float bfhi(unsigned w) { return __uint_as_float(w & 0xffff0000u); }
; __global__ void __launch_bounds__(NTHR, 2) hybrid_fwd(Params p) {
;     ...
;                 if (split && step == 1) {
;                     const bf16* P0 = (const bf16*)(ws + WS_HL); const bf16* P1 = P0 + (size_t)MT * DM; bf16* MG = (bf16*)(ws + WS_PP);
;                     for (int it = c * NTHR + (int)threadIdx.x; it < 1024 * 256; it += G * NTHR) { const size_t r = (size_t)(NP + (it >> 8)); const int c8 = (it & 255) * 8;
;                         const v4u a = *(const v4u*)(P0 + r * DM + c8), b = *(const v4u*)(P1 + r * DM + c8), gq = *(const v4u*)(PROJ + r * NC + C_MB + c8);
;                         v4u o;
;                         o.x = pk2(fmaxf(bflo(gq.x), 1e-30f) * (bflo(a.x) + bflo(b.x)), fmaxf(bfhi(gq.x), 1e-30f) * (bfhi(a.x) + bfhi(b.x)));
;                         o.y = pk2(fmaxf(bflo(gq.y), 1e-30f) * (bflo(a.y) + bflo(b.y)), fmaxf(bfhi(gq.y), 1e-30f) * (bfhi(a.y) + bfhi(b.y)));
;                         o.z = pk2(fmaxf(bflo(gq.z), 1e-30f) * (bflo(a.z) + bflo(b.z)), fmaxf(bfhi(gq.z), 1e-30f) * (bfhi(a.z) + bfhi(b.z)));
;                         o.w = pk2(fmaxf(bflo(gq.w), 1e-30f) * (bflo(a.w) + bflo(b.w)), fmaxf(bfhi(gq.w), 1e-30f) * (bfhi(a.w) + bfhi(b.w)));
;                         *(v4u*)(MG + r * DM + c8) = o; }
;                     xcd_barrier(bar);
.LBB0_915:
	s_cmp_lg_u32 s51, 1
	v_readlane_b32 s2, v249, 58
	s_cselect_b64 s[0:1], -1, 0
	v_readlane_b32 s3, v249, 59
	s_or_b64 s[0:1], s[2:3], s[0:1]
	s_and_b64 vcc, exec, s[0:1]
	s_branch .LBB0_715
	s_mov_b64 s[0:1], exec
	v_readlane_b32 s2, v248, 10
	v_readlane_b32 s3, v248, 11
	s_and_b64 s[2:3], s[0:1], s[2:3]
	s_mov_b64 exec, s[2:3]
	s_cbranch_execz .LBB0_919
	s_mov_b64 s[18:19], 0
	v_mov_b32_e32 v2, v209
	v_mov_b32_e32 v3, v207
.LBB0_918:
	v_ashrrev_i32_e32 v0, 8, v3
	v_add_u32_e32 v12, 0x2000, v0
	v_ashrrev_i32_e32 v13, 31, v12
	v_and_b32_e32 v0, 0x7f8, v2
	v_mov_b64_e32 v[14:15], s[8:9]
	v_lshlrev_b64 v[16:17], 12, v[12:13]
	v_lshlrev_b32_e32 v0, 1, v0
	v_mad_i64_i32 v[12:13], s[2:3], v12, s25, v[14:15]
	v_lshl_add_u64 v[12:13], v[12:13], 0, v[0:1]
	v_lshl_add_u64 v[4:5], s[46:47], 0, v[16:17]
	v_lshl_add_u64 v[8:9], s[56:57], 0, v[16:17]
	v_add_co_u32_e32 v12, vcc, s22, v12
	v_lshl_add_u64 v[4:5], v[4:5], 0, v[0:1]
	v_lshl_add_u64 v[8:9], v[8:9], 0, v[0:1]
	v_addc_co_u32_e32 v13, vcc, 0, v13, vcc
	global_load_dwordx4 v[4:7], v[4:5], off
	s_mov_b32 s2, 0x1ffff
	global_load_dwordx4 v[8:11], v[8:9], off
	v_cmp_lt_i32_e32 vcc, s2, v3
	global_load_dwordx4 v[12:15], v[12:13], off
	v_add_u32_e32 v2, 0x100000, v2
	s_or_b64 s[18:19], vcc, s[18:19]
	s_waitcnt vmcnt(0) lgkmcnt(0)
	v_lshlrev_b32_e32 v21, 16, v5
	v_lshlrev_b32_e32 v20, 16, v4
	v_lshlrev_b32_e32 v23, 16, v9
	v_lshlrev_b32_e32 v22, 16, v8
	v_lshlrev_b32_e32 v18, 16, v12
	v_and_b32_e32 v12, 0xffff0000, v12
	v_lshlrev_b32_e32 v19, 16, v13
	v_and_b32_e32 v13, 0xffff0000, v13
	v_and_b32_e32 v5, 0xffff0000, v5
	v_and_b32_e32 v4, 0xffff0000, v4
	v_and_b32_e32 v9, 0xffff0000, v9
	v_and_b32_e32 v8, 0xffff0000, v8
	v_max_f32_e32 v12, v12, v12
	v_max_f32_e32 v13, v13, v13
	v_pk_add_f32 v[4:5], v[4:5], v[8:9]
	v_and_b32_e32 v9, 0xffff0000, v14
	v_max_f32_e32 v18, v18, v18
	v_max_f32_e32 v12, 0xda24260, v12
	v_max_f32_e32 v19, v19, v19
	v_max_f32_e32 v13, 0xda24260, v13
	v_max_f32_e32 v9, v9, v9
	v_max_f32_e32 v18, 0xda24260, v18
	v_max_f32_e32 v19, 0xda24260, v19
	v_pk_add_f32 v[20:21], v[20:21], v[22:23]
	v_pk_mul_f32 v[4:5], v[4:5], v[12:13]
	v_lshlrev_b32_e32 v8, 16, v14
	v_max_f32_e32 v12, 0xda24260, v9
	v_lshlrev_b32_e32 v9, 16, v15
	v_and_b32_e32 v13, 0xffff0000, v15
	v_pk_mul_f32 v[18:19], v[20:21], v[18:19]
	v_max_f32_e32 v8, v8, v8
	v_max_f32_e32 v9, v9, v9
	v_max_f32_e32 v13, v13, v13
	v_lshlrev_b32_e32 v15, 16, v7
	v_lshlrev_b32_e32 v14, 16, v6
	v_lshlrev_b32_e32 v21, 16, v11
	v_lshlrev_b32_e32 v20, 16, v10
	v_and_b32_e32 v7, 0xffff0000, v7
	v_and_b32_e32 v6, 0xffff0000, v6
	v_and_b32_e32 v11, 0xffff0000, v11
	v_and_b32_e32 v10, 0xffff0000, v10
	v_max_f32_e32 v8, 0xda24260, v8
	v_max_f32_e32 v9, 0xda24260, v9
	v_max_f32_e32 v13, 0xda24260, v13
	v_pk_add_f32 v[14:15], v[14:15], v[20:21]
	v_pk_add_f32 v[6:7], v[6:7], v[10:11]
	v_pk_mul_f32 v[8:9], v[14:15], v[8:9]
	v_pk_mul_f32 v[6:7], v[6:7], v[12:13]
	v_bfe_u32 v12, v5, 16, 1
	v_bfe_u32 v13, v4, 16, 1
	v_add3_u32 v4, v4, v13, s26
	v_add3_u32 v5, v5, v12, s26
	v_bfe_u32 v12, v8, 16, 1
	v_bfe_u32 v13, v9, 16, 1
	v_bfe_u32 v10, v7, 16, 1
	v_bfe_u32 v11, v6, 16, 1
	v_add3_u32 v9, v9, v13, s26
	v_add3_u32 v8, v8, v12, s26
	v_add3_u32 v6, v6, v11, s26
	v_add3_u32 v7, v7, v10, s26
	v_bfe_u32 v10, v18, 16, 1
	v_bfe_u32 v11, v19, 16, 1
	v_lshrrev_b32_e32 v8, 16, v8
	v_lshrrev_b32_e32 v9, 16, v9
	v_add3_u32 v11, v19, v11, s26
	v_add3_u32 v10, v18, v10, s26
	v_and_or_b32 v7, v7, s24, v9
	v_and_or_b32 v6, v6, s24, v8
	v_lshl_add_u64 v[8:9], s[58:59], 0, v[16:17]
	v_lshrrev_b32_e32 v10, 16, v10
	v_lshrrev_b32_e32 v11, 16, v11
	v_lshl_add_u64 v[8:9], v[8:9], 0, v[0:1]
	v_add_u32_e32 v0, 0x20000, v3
	v_and_or_b32 v5, v5, s24, v11
	v_and_or_b32 v4, v4, s24, v10
	v_mov_b32_e32 v3, v0
	global_store_dwordx4 v[8:9], v[4:7], off
	s_andn2_b64 exec, exec, s[18:19]
	s_cbranch_execnz .LBB0_918
